# v17 plus 64-byte alignment of the streaming loop heads (mod/rope, convert, final norm loops)
# speedup vs baseline: 1.0014x; 1.0014x over previous
; DEVI float siluf_(float x) { return x * __builtin_amdgcn_rcpf(1.0f + __expf(-x)); }
; DEVI void phase_mod_rope(const Params& p, unsigned char* smem, int bid, int nb) {
;     ...
;     const float* c = (const float*)p.in[1];
;     for (int i = tid; i < D; i += NT) sc[i] = siluf_(c[i]);
.LBB0_2:
	s_or_b64 exec, exec, s[4:5]
	s_load_dwordx16 s[12:27], s[0:1], 0x0
	v_mov_b32_e32 v4, v199
	s_movk_i32 s2, 0x800
	s_mov_b64 s[6:7], 0
	s_mov_b64 s[4:5], 0
	v_cmp_gt_i32_e32 vcc, s2, v4
	s_and_saveexec_b64 s[8:9], vcc
	s_cbranch_execz .LBB0_5
	s_waitcnt lgkmcnt(0)
	v_mov_b32_e32 v2, s14
	v_mov_b32_e32 v3, s15
	v_ashrrev_i32_e32 v5, 31, v4
	v_add_u32_e32 v1, 0xfffffe00, v4
	v_lshl_add_u32 v6, v4, 2, 0
	v_lshl_add_u64 v[2:3], v[4:5], 2, v[2:3]
	s_mov_b64 s[10:11], 0x800
	s_movk_i32 s2, 0x5ff
	.p2alignl 6, 3212836864

; DEVI void phase_mod_rope(const Params& p, unsigned char* smem, int bid, int nb) {
;     ...
;     const float invf[16] = {1.000000000e+00f, 4.403665960e-01f, 1.939227432e-01f, 8.539710194e-02f, 3.760603070e-02f, 1.656043902e-02f, 7.292664610e-03f, 3.211445874e-03f,
;                             1.414213562e-03f, 6.227723788e-04f, 2.742481884e-04f, 1.207697351e-04f, 5.318296098e-05f, 2.341999971e-05f, 1.031338616e-05f, 4.541670478e-06f};
;     const int* pos = (const int*)p.in[2];
;     float* cosT = (float*)(ws_ + OFF_COS); float* sinT = (float*)(ws_ + OFF_SIN);
;     for (int e = bid * NT + tid; e < S * 16; e += nb * NT) {
;         const int t = e >> 4, i = e & 15;
;         float fi = invf[0];
; #pragma unroll
;         for (int j = 1; j < 16; ++j) fi = (i == j) ? invf[j] : fi;
;         const float ang = (float)pos[t] * fi;
;         const double a = (double)ang;
;         const double kq = __builtin_rint(a * 0.15915494309189535);
;         const double r = a - kq * 6.283185307179586;
;         const double y = r * 0.25, y2 = y * y;
;         double s = y * (1.0 - y2 / 6.0 * (1.0 - y2 / 20.0 * (1.0 - y2 / 42.0 * (1.0 - y2 / 72.0 * (1.0 - y2 / 110.0 * (1.0 - y2 / 156.0))))));
;         double cc = 1.0 - y2 / 2.0 * (1.0 - y2 / 12.0 * (1.0 - y2 / 30.0 * (1.0 - y2 / 56.0 * (1.0 - y2 / 90.0 * (1.0 - y2 / 132.0 * (1.0 - y2 / 182.0))))));
;         double s2 = 2.0 * s * cc, c2 = 1.0 - 2.0 * s * s;
;         double s4 = 2.0 * s2 * c2, c4 = 1.0 - 2.0 * s2 * s2;
;         cosT[e] = (float)c4; sinT[e] = (float)s4;
.LBB0_12:
	s_lshl_b32 s0, s82, 9
	v_writelane_b32 v252, s0, 54
	v_add_u32_e32 v2, s0, v4
	s_mov_b32 s0, 0x40000
	v_cmp_gt_i32_e32 vcc, s0, v2
	s_and_saveexec_b64 s[24:25], vcc
	v_readlane_b32 s36, v252, 6
	v_readlane_b32 s37, v252, 7
	v_readlane_b32 s40, v252, 10
	v_readlane_b32 s41, v252, 11
	v_readlane_b32 s46, v252, 16
	v_readlane_b32 s47, v252, 17
	v_readlane_b32 s48, v252, 18
	v_readlane_b32 s49, v252, 19
	v_readlane_b32 s50, v252, 20
	v_readlane_b32 s51, v252, 21
	v_readlane_b32 s38, v252, 8
	v_readlane_b32 s39, v252, 9
	v_readlane_b32 s42, v252, 12
	v_readlane_b32 s43, v252, 13
	v_readlane_b32 s44, v252, 14
	v_readlane_b32 s45, v252, 15
	s_cbranch_execz .LBB0_15
	v_and_b32_e32 v1, 15, v4
	v_mov_b32_e32 v3, 0x3ee177bb
	v_cmp_eq_u32_e32 vcc, 1, v1
	v_mov_b32_e32 v4, 0x3e4693af
	s_lshl_b32 s26, s90, 9
	v_cndmask_b32_e32 v3, 1.0, v3, vcc
	v_cmp_ne_u32_e32 vcc, 2, v1
	s_add_u32 s0, s88, s4
	s_addc_u32 s1, s89, s5
	v_cndmask_b32_e32 v3, v4, v3, vcc
	v_mov_b32_e32 v4, 0x3daee4ad
	v_cmp_ne_u32_e32 vcc, 3, v1
	s_ashr_i32 s27, s26, 31
	s_mov_b32 s34, 0x6dc9c883
	v_cndmask_b32_e32 v3, v4, v3, vcc
	v_mov_b32_e32 v4, 0x3d1a08c8
	v_cmp_ne_u32_e32 vcc, 4, v1
	s_mov_b32 s2, 0x54442d18
	s_mov_b32 s38, 0
	v_cndmask_b32_e32 v3, v4, v3, vcc
	v_mov_b32_e32 v4, 0x3c87a9c2
	v_cmp_ne_u32_e32 vcc, 5, v1
	s_mov_b32 s42, 0
	s_mov_b32 s44, 0
	v_cndmask_b32_e32 v3, v4, v3, vcc
	v_mov_b32_e32 v4, 0x3beef74e
	v_cmp_ne_u32_e32 vcc, 6, v1
	s_mov_b32 s78, 0
	s_mov_b32 s80, 0
	v_cndmask_b32_e32 v3, v4, v3, vcc
	v_mov_b32_e32 v4, 0x3b52771f
	v_cmp_ne_u32_e32 vcc, 7, v1
	s_mov_b32 s84, 0
	s_mov_b32 s86, 0
	v_cndmask_b32_e32 v3, v4, v3, vcc
	v_mov_b32_e32 v4, 0x3ab95d22
	v_cmp_ne_u32_e32 vcc, 8, v1
	s_mov_b32 s68, 0
	s_mov_b32 s70, 0
	v_cndmask_b32_e32 v3, v4, v3, vcc
	v_mov_b32_e32 v4, 0x3a23418c
	v_cmp_ne_u32_e32 vcc, 9, v1
	s_mov_b32 s72, 0
	s_mov_b32 s74, 0
	v_cndmask_b32_e32 v3, v4, v3, vcc
	v_mov_b32_e32 v4, 0x398fc8f8
	v_cmp_ne_u32_e32 vcc, 10, v1
	s_mov_b32 s76, 0
	s_lshl_b64 s[28:29], s[26:27], 2
	v_cndmask_b32_e32 v3, v4, v3, vcc
	v_mov_b32_e32 v4, 0x38fd45c2
	v_cmp_ne_u32_e32 vcc, 11, v1
	s_mov_b64 s[30:31], 0
	s_mov_b32 s35, 0x3fc45f30
	v_cndmask_b32_e32 v3, v4, v3, vcc
	v_mov_b32_e32 v4, 0x385f10c5
	v_cmp_ne_u32_e32 vcc, 12, v1
	s_mov_b32 s3, 0xc01921fb
	s_mov_b32 s39, 0xc0180000
	v_cndmask_b32_e32 v3, v4, v3, vcc
	v_mov_b32_e32 v4, 0x37c47611
	v_cmp_ne_u32_e32 vcc, 13, v1
	s_mov_b32 s43, 0xc0340000
	s_mov_b32 s45, 0xc0450000
	v_cndmask_b32_e32 v3, v4, v3, vcc
	v_mov_b32_e32 v4, 0x372d07a8
	v_cmp_ne_u32_e32 vcc, 14, v1
	s_mov_b32 s79, 0xc0520000
	s_mov_b32 s81, 0xc05b8000
	v_cndmask_b32_e32 v3, v4, v3, vcc
	v_mov_b32_e32 v4, 0x369864a7
	v_cmp_ne_u32_e32 vcc, 15, v1
	s_mov_b32 s85, 0xc0638000
	s_mov_b32 s87, 0xc0280000
	v_cndmask_b32_e32 v1, v4, v3, vcc
	v_ashrrev_i32_e32 v3, 31, v2
	v_lshl_add_u64 v[4:5], v[2:3], 2, s[0:1]
	s_mov_b64 s[0:1], 0x39f58000
	v_lshl_add_u64 v[4:5], v[4:5], 0, s[0:1]
	s_mov_b32 s69, 0xc03e0000
	s_mov_b32 s71, 0xc04c0000
	s_mov_b32 s73, 0xc0568000
	s_mov_b32 s75, 0xc0608000
	s_mov_b32 s77, 0xc066c000
	.p2alignl 6, 3212836864

; DEVI bf16_t f2bf(float f) { return (bf16_t)cvt_pk_bf16(f, 0.f); }
; DEVI void phase_convert(const Params& p, int l, unsigned char* smem, int bid, int nb) {
;     ...
;     {
;         int tl_ = threadIdx.x; asm volatile("" : "+v"(tl_)); int ll_ = l; asm volatile("" : "+s"(ll_));
;         size_t wzz_ = 0; asm volatile("" : "+s"(wzz_));
;         bf16_t* WT = (bf16_t*)(ws + wzz_ + OFF_LORA);
;         const float* w2 = (const float*)p.in[12] + (size_t)ll_ * 96 * 512; const float* a2 = (const float*)p.in[14] + (size_t)ll_ * 96 * 512; const float* g2 = (const float*)p.in[15] + (size_t)ll_ * 256 * 512;
;         for (int k = bid; k < 448; k += nb) {
;             const int n = tl_;
;             const float v = k < 96 ? w2[k * 512 + n] : (k < 192 ? a2[(k - 96) * 512 + n] : g2[(k - 192) * 512 + n]);
;             WT[n * 448 + k] = f2bf(v);
;         }
; __global__ void __launch_bounds__(512, 2) fwd_megakernel(Params p) {
;     ...
;     __syncthreads();
.LBB0_15:
	s_or_b64 exec, exec, s[24:25]
	s_cmpk_lt_i32 s82, 0x1c0
	s_cselect_b64 s[4:5], -1, 0
	v_writelane_b32 v252, s4, 55
	s_movk_i32 s2, 0x1c0
	v_mov_b32_e32 v2, v199
	s_mov_b32 s8, 0
	s_mov_b64 s[0:1], 0
	v_writelane_b32 v252, s5, 56
	s_and_b64 vcc, exec, s[4:5]
	s_barrier
	s_cbranch_vccz .LBB0_35
	s_add_u32 s0, s88, s0
	s_addc_u32 s1, s89, s1
	s_add_u32 s0, s0, 0x3a1f8000
	v_readlane_b32 s12, v252, 22
	s_addc_u32 s1, s1, 0
	s_ashr_i32 s9, s8, 31
	s_mul_i32 s6, s8, 0x30000
	v_readlane_b32 s20, v252, 30
	s_mul_hi_i32 s3, s8, 0x30000
	v_readlane_b32 s21, v252, 31
	s_add_u32 s4, s20, s6
	v_readlane_b32 s24, v252, 34
	s_addc_u32 s5, s21, s3
	v_readlane_b32 s25, v252, 35
	s_add_u32 s6, s24, s6
	v_readlane_b32 s26, v252, 36
	s_addc_u32 s7, s25, s3
	s_lshl_b64 s[8:9], s[8:9], 19
	v_readlane_b32 s27, v252, 37
	s_add_u32 s8, s26, s8
	s_addc_u32 s9, s27, s9
	s_add_i32 s83, s82, 1
	v_mul_lo_u32 v10, v2, s2
	s_max_i32 s2, s83, 0x1c0
	s_sub_i32 s2, s2, s82
	v_readlane_b32 s13, v252, 23
	s_cmp_lt_u32 s2, 4
	v_readlane_b32 s16, v252, 26
	s_cselect_b64 s[12:13], -1, 0
	v_add_u32_e32 v4, 0xfffe8000, v2
	s_and_b64 vcc, exec, s[12:13]
	v_readlane_b32 s16, v252, 54
	v_readlane_b32 s14, v252, 24
	v_readlane_b32 s15, v252, 25
	v_readlane_b32 s17, v252, 27
	v_readlane_b32 s18, v252, 28
	v_readlane_b32 s19, v252, 29
	v_readlane_b32 s22, v252, 32
	v_readlane_b32 s23, v252, 33
	s_cbranch_vccnz .LBB0_22
	v_cvt_f32_u32_e32 v1, s90
	s_cmp_eq_u32 s90, 1
	s_cselect_b64 s[10:11], -1, 0
	s_add_i32 s3, s82, s90
	v_rcp_iflag_f32_e32 v1, v1
	s_max_i32 s12, s3, 0x1c0
	s_cmpk_lt_i32 s3, 0x1c0
	s_cselect_b64 vcc, -1, 0
	v_mul_f32_e32 v1, 0x4f7ffffe, v1
	v_cvt_u32_f32_e32 v1, v1
	s_cmp_lg_u64 vcc, 0
	s_addc_u32 s3, s82, s90
	s_sub_i32 s3, s12, s3
	s_sub_i32 s12, 0, s90
	v_readfirstlane_b32 s13, v1
	s_mul_i32 s12, s12, s13
	s_mul_hi_u32 s12, s13, s12
	s_add_i32 s13, s13, s12
	s_mul_hi_u32 s12, s3, s13
	s_mul_i32 s13, s12, s90
	s_sub_i32 s3, s3, s13
	s_add_i32 s13, s12, 1
	s_sub_i32 s14, s3, s90
	s_cmp_ge_u32 s3, s90
	s_cselect_b32 s12, s13, s12
	s_cselect_b32 s3, s14, s3
	s_add_i32 s13, s12, 1
	s_cmp_ge_u32 s3, s90
	s_cselect_b32 s3, s13, s12
	v_add_u32_e32 v6, s82, v10
	v_mov_b32_e32 v1, s3
	v_addc_co_u32_e32 v1, vcc, v6, v1, vcc
	v_cmp_ge_i32_e32 vcc, v1, v6
	s_and_b64 s[14:15], s[10:11], vcc
	s_mov_b64 s[12:13], -1
	v_mov_b32_e32 v1, s82
	v_mov_b32_e32 v3, s16
	s_and_saveexec_b64 s[10:11], s[14:15]
	s_cbranch_execz .LBB0_25
	v_add_u32_e32 v8, 0xffff4000, v2
	s_and_b32 s3, s2, -2
	v_mov_b32_e32 v1, v4
	v_mov_b32_e32 v3, v8
	v_mov_b32_e32 v5, v2
	s_mov_b32 s14, s6
	s_mov_b32 s15, s7
	s_mov_b32 s16, s8
	s_mov_b32 s17, s9
	s_mov_b32 s18, s4
	s_mov_b32 s19, s5
	s_mov_b32 s20, s3
	s_mov_b64 s[12:13], s[82:83]
	.p2alignl 6, 3212836864

; DEVI bf16_t f2bf(float f) { return (bf16_t)cvt_pk_bf16(f, 0.f); }
; DEVI void phase_convert(const Params& p, int l, unsigned char* smem, int bid, int nb) {
;     ...
;         for (int k = bid; k < 448; k += nb) {
;             const int n = tl_;
;             const float v = k < 96 ? w2[k * 512 + n] : (k < 192 ? a2[(k - 96) * 512 + n] : g2[(k - 192) * 512 + n]);
;             WT[n * 448 + k] = f2bf(v);
.LBB0_27:
	s_or_b64 exec, exec, s[14:15]
	v_ashrrev_i32_e32 v9, 31, v8
	v_lshl_add_u64 v[6:7], v[8:9], 2, v[6:7]
	global_load_dword v5, v[6:7], off
	v_add_u32_e32 v6, v10, v1
	v_add_u32_e32 v1, s90, v1
	v_ashrrev_i32_e32 v7, 31, v6
	v_cmp_lt_i32_e32 vcc, s19, v1
	v_lshl_add_u64 v[6:7], v[6:7], 1, s[0:1]
	s_or_b64 s[12:13], vcc, s[12:13]
	v_add_u32_e32 v3, s2, v3
	s_waitcnt vmcnt(0)
	v_cvt_pk_bf16_f32 v5, v5, s0
	global_store_short v[6:7], v5, off
	s_andn2_b64 exec, exec, s[12:13]
	s_cbranch_execz .LBB0_34
	.p2alignl 6, 3212836864

; DEVI void phase_convert(const Params& p, int l, unsigned char* smem, int bid, int nb) {
;     ...
;     for (int it = bid; it < c7; it += nb) {
;         if (it < c0) { conv_tile(smem, (const float*)p.in[6] + (size_t)l * D * IN_TOTAL, IN_TOTAL, D, (bf16_t*)(ws + OFF_WIN), 0, it / 32, it % 32); }
;         else if (it < c1) { const int j = it - c0; conv_tile(smem, (const float*)p.in[24] + (size_t)l * 512 * D, D, 512, (bf16_t*)(ws + OFF_WBA), 2, j / 8, j % 8); }
;         else if (it < c2) { const int j = it - c1; conv_tile(smem, (const float*)p.in[25] + (size_t)l * 256 * D, D, 256, (bf16_t*)(ws + OFF_WBB), 2, j / 4, j % 4); }
;         else if (it < c3) { const int j = it - c2; conv_tile(smem, (const float*)p.in[26] + (size_t)l * 512 * D, D, 512, (bf16_t*)(ws + OFF_WBC), 2, j / 8, j % 8); }
;         else if (it < c4) { const int j = it - c3; conv_tile(smem, (const float*)p.in[27] + (size_t)l * 512 * D, D, 512, (bf16_t*)(ws + OFF_WBD), 2, j / 8, j % 8); }
;         else if (it < c5) { const int j = it - c4; conv_tile(smem, (const float*)p.in[28] + (size_t)l * D * D, D, D, (bf16_t*)(ws + OFF_WOUT), 2, j / 32, j % 32); }
;         else if (it < c6) { const int j = it - c5; conv_tile(smem, (const float*)p.in[30] + (size_t)l * D * 2 * FFN_H, 2 * FFN_H, D, (bf16_t*)(ws + OFF_WF1), 1, j / 32, j % 32); }
;         else { const int j = it - c6; conv_tile(smem, (const float*)p.in[31] + (size_t)l * FFN_H * D, D, FFN_H, (bf16_t*)(ws + OFF_WF2), 2, j / 88, j % 88); }
;     }
.LBB0_38:
	s_add_i32 s18, s18, s90
	s_add_i32 s3, s3, s8
	s_add_i32 s9, s9, s10
	s_add_i32 s11, s11, s12
	s_add_i32 s13, s13, s14
	s_cmpk_lt_i32 s18, 0x4780
	s_cbranch_scc0 .LBB0_96
	.p2alignl 6, 3212836864

; __global__ void __launch_bounds__(512, 2) fwd_megakernel(Params p) {
;     ...
;     grid.sync();
.LBB0_102:
	s_or_b64 exec, exec, s[6:7]
	v_mov_b32_e32 v0, 0
	global_load_dword v2, v0, s[4:5] offset:32 sc1
	v_and_b32_e32 v1, 0xffff0000, v1
	s_waitcnt vmcnt(0)
	v_and_b32_e32 v2, 0xffff0000, v2
	v_cmp_eq_u32_e32 vcc, v2, v1
	s_and_saveexec_b64 s[6:7], vcc
	s_cbranch_execz .LBB0_105
	s_mov_b64 s[8:9], 0
	.p2alignl 6, 3212836864

; DEVI void phase_final_norm(float* x, const float* gain, int bid, int nb) {
;     int tid_ = threadIdx.x; asm volatile("" : "+v"(tid_));
;     const int wid = tid_ >> 6, lane = tid_ & 63;
;     for (int row = bid * 8 + wid; row < S; row += nb * 8) {
;         f32x4* xr = (f32x4*)(x + (size_t)row * D);
;         f32x4 v[8]; float ss = 0.f;
; #pragma unroll
;         for (int i = 0; i < 8; ++i) { v[i] = xr[lane + 64 * i]; ss += v[i][0] * v[i][0] + v[i][1] * v[i][1] + v[i][2] * v[i][2] + v[i][3] * v[i][3]; }
;         ss = wave_sum(ss);
;         const float r = rsqrtf(ss * (1.0f / D) + 1e-6f);
; #pragma unroll
;         for (int i = 0; i < 8; ++i) xr[lane + 64 * i] = v[i] * r * ((const f32x4*)gain)[lane + 64 * i];
.LBB0_1004:
	v_readlane_b32 s4, v255, 26
	v_ashrrev_i32_e32 v10, 6, v199
	s_movk_i32 s0, 0x4000
	v_add_u32_e32 v12, s4, v10
	v_readlane_b32 s5, v255, 27
	v_cmp_gt_i32_e32 vcc, s0, v12
	s_and_saveexec_b64 s[0:1], vcc
	s_cbranch_execz .LBB0_1007
	v_cmp_lt_i32_e32 vcc, v209, v203
	v_ashrrev_i32_e32 v11, 31, v10
	v_lshl_add_u64 v[10:11], v[10:11], 0, s[4:5]
	v_cndmask_b32_e32 v0, v202, v209, vcc
	v_cmp_lt_i32_e32 vcc, v208, v203
	v_lshlrev_b32_e32 v13, 2, v0
	v_mov_b32_e32 v21, 0
	v_cndmask_b32_e32 v0, v202, v208, vcc
	v_cmp_lt_i32_e32 vcc, v200, v203
	v_lshlrev_b32_e32 v14, 2, v0
	v_readlane_b32 s0, v252, 0
	v_cndmask_b32_e32 v0, v202, v200, vcc
	v_cmp_lt_i32_e32 vcc, v211, v203
	v_lshlrev_b32_e32 v15, 2, v0
	v_lshlrev_b64 v[10:11], 13, v[10:11]
	v_cndmask_b32_e32 v0, v202, v211, vcc
	v_cmp_lt_i32_e32 vcc, v205, v203
	v_lshlrev_b32_e32 v16, 2, v0
	v_readlane_b32 s1, v252, 1
	v_cndmask_b32_e32 v0, v202, v205, vcc
	v_cmp_lt_i32_e32 vcc, v204, v203
	v_lshlrev_b32_e32 v17, 2, v0
	v_readlane_b32 s2, v252, 2
	v_cndmask_b32_e32 v0, v202, v204, vcc
	v_lshlrev_b32_e32 v18, 2, v0
	v_lshlrev_b32_e32 v0, 4, v199
	v_and_b32_e32 v20, 0x3f0, v0
	v_readlane_b32 s3, v252, 3
	v_or_b32_e32 v2, 0x1000, v20
	v_mov_b32_e32 v3, v21
	v_or_b32_e32 v4, 0x1400, v20
	v_mov_b32_e32 v5, v21
	v_or_b32_e32 v6, 0x1800, v20
	v_mov_b32_e32 v7, v21
	v_or_b32_e32 v8, 0x1c00, v20
	v_mov_b32_e32 v9, v21
	v_or_b32_e32 v10, v10, v20
	v_lshl_add_u64 v[0:1], s[0:1], 0, v[20:21]
	v_lshl_add_u64 v[2:3], s[0:1], 0, v[2:3]
	v_lshl_add_u64 v[4:5], s[0:1], 0, v[4:5]
	v_lshl_add_u64 v[6:7], s[0:1], 0, v[6:7]
	v_lshl_add_u64 v[8:9], s[0:1], 0, v[8:9]
	v_lshl_add_u64 v[10:11], s[2:3], 0, v[10:11]
	s_mov_b64 s[0:1], 0x1000
	v_lshl_add_u64 v[10:11], v[10:11], 0, s[0:1]
	s_mov_b64 s[0:1], 0
	v_mov_b32_e32 v19, 0x358637bd
	s_mov_b32 s2, 0x800000
	s_movk_i32 s3, 0x3fff
	global_load_dwordx4 v[220:223], v[0:1], off
	global_load_dwordx4 v[224:227], v[0:1], off offset:1024
	global_load_dwordx4 v[228:231], v[0:1], off offset:2048
	global_load_dwordx4 v[232:235], v[0:1], off offset:3072
	global_load_dwordx4 v[236:239], v[2:3], off
	global_load_dwordx4 v[240:243], v[4:5], off
	global_load_dwordx4 v[244:247], v[6:7], off
	global_load_dwordx4 v[248:251], v[8:9], off
	.p2alignl 6, 3212836864
